# speedup vs baseline: 1.0095x; 1.0008x over previous
; #define PG8_STAGE(bufoff, gbase, voff) do { _Pragma("unroll") for (int _i = 0; _i < 2; ++_i) \
;         __builtin_amdgcn_global_load_lds((const unsigned*)((const char*)(gbase) + (voff)[_i]), (LAS unsigned*)(lds + (bufoff) + ldsw + _i * 8192), 16, 0, 0); } while (0)
; #define PG8_LDA(dst, b, h) do { _Pragma("unroll") for (int m = 0; m < 4; ++m) _Pragma("unroll") for (int k = 0; k < 2; ++k) dst[m][k] = *(const LAS bf16x8*)(lds + PG8_SA(b, h) + aoff + m * 2048 + k * 1024); } while (0)
; #define PG8_LDB(dst, b, h) do { _Pragma("unroll") for (int n = 0; n < 2; ++n) _Pragma("unroll") for (int k = 0; k < 2; ++k) dst[n][k] = *(const LAS bf16x8*)(lds + PG8_SB(b, h) + boff + n * 2048 + k * 1024); } while (0)
; #define PG8_MMA(ai, bj, At, Bt) do { __builtin_amdgcn_s_setprio(1); _Pragma("unroll") for (int m = 0; m < 4; ++m) _Pragma("unroll") for (int n = 0; n < 2; ++n) _Pragma("unroll") for (int k = 0; k < 2; ++k) \
;         acc[ai][bj][m][n] = __builtin_amdgcn_mfma_f32_16x16x32_bf16(Bt[n][k], At[m][k], acc[ai][bj][m][n], 0, 0, 0); __builtin_amdgcn_s_setprio(0); } while (0)
; #define PG8_WAIT_L(n) asm volatile("s_waitcnt lgkmcnt(" #n ")" ::: "memory")
; #define PG8_BAR __builtin_amdgcn_s_barrier()
; #define PG8_SCHED __builtin_amdgcn_sched_barrier(0)
; __device__ __forceinline__ void gemm_phase(LAS unsigned char* lds, const GemmD& g) {
;     ...
;         for (int t = 0; t < nt; t += 2) {
;             const bool last = (t == nt - 2);
;             const char* a1 = cA + (size_t)(t + 1) * kstep;
;             const char* a2 = last ? nA : cA + (size_t)(t + 2) * kstep; const char* b2 = last ? nB : cB + (size_t)(t + 2) * kstep;
;             const char* a3 = a2 + kstep; const char* b3 = b2 + kstep;
;             PG8_LDB(B0, 0, 0); PG8_SCHED; PG8_LDA(At, 0, 0); PG8_STAGE(PG8_SA(1, 1), a1 + hstep, voffA);
;             PG8_WAIT_L(8); PG8_BAR; PG8_WAIT_L(0); PG8_MMA(0, 0, At, B0); PG8_BAR; PG8_SCHED;
.LBB0_145:
	ds_read_b128 v[136:139], v244
	ds_read_b128 v[140:143], v244 offset:1024
	ds_read_b128 v[144:147], v244 offset:2048
	ds_read_b128 v[148:151], v244 offset:3072
	s_add_i32 m0, s2, 0xc000
	ds_read_b128 v[152:155], v233
	ds_read_b128 v[156:159], v233 offset:1024
	ds_read_b128 v[160:163], v233 offset:2048
	ds_read_b128 v[184:187], v233 offset:3072
	ds_read_b128 v[188:191], v233 offset:4096
	ds_read_b128 v[192:195], v233 offset:5120
	ds_read_b128 v[196:199], v233 offset:6144
	ds_read_b128 v[200:203], v233 offset:7168
	global_load_lds_dwordx4 v174, s[98:99]
	s_add_i32 m0, s2, 0xe000
	s_nop 0
	global_load_lds_dwordx4 v176, s[98:99]
	s_waitcnt lgkmcnt(8)
	s_barrier
	s_waitcnt lgkmcnt(0)
	v_mfma_f32_16x16x32_bf16 v[126:129], v[136:139], v[152:155], v[126:129]
	v_mfma_f32_16x16x32_bf16 v[122:125], v[144:147], v[152:155], v[122:125]
	v_mfma_f32_16x16x32_bf16 v[110:113], v[136:139], v[160:163], v[110:113]
	v_mfma_f32_16x16x32_bf16 v[106:109], v[144:147], v[160:163], v[106:109]
	v_mfma_f32_16x16x32_bf16 v[94:97], v[136:139], v[188:191], v[94:97]
	v_mfma_f32_16x16x32_bf16 v[90:93], v[144:147], v[188:191], v[90:93]
	v_mfma_f32_16x16x32_bf16 v[78:81], v[136:139], v[196:199], v[78:81]
	v_mfma_f32_16x16x32_bf16 v[74:77], v[144:147], v[196:199], v[74:77]
	v_mfma_f32_16x16x32_bf16 v[126:129], v[140:143], v[156:159], v[126:129]
	v_mfma_f32_16x16x32_bf16 v[122:125], v[148:151], v[156:159], v[122:125]
	v_mfma_f32_16x16x32_bf16 v[110:113], v[140:143], v[184:187], v[110:113]
	v_mfma_f32_16x16x32_bf16 v[106:109], v[148:151], v[184:187], v[106:109]
	v_mfma_f32_16x16x32_bf16 v[94:97], v[140:143], v[192:195], v[94:97]
	v_mfma_f32_16x16x32_bf16 v[90:93], v[148:151], v[192:195], v[90:93]
	v_mfma_f32_16x16x32_bf16 v[78:81], v[140:143], v[200:203], v[78:81]
	v_mfma_f32_16x16x32_bf16 v[74:77], v[148:151], v[200:203], v[74:77]
	s_barrier
	v_cmp_eq_u32_e32 vcc, s4, v135
	s_add_i32 s5, s4, 2
	s_cbranch_vccz .Lkl_notlast
	v_readfirstlane_b32 s98, v180
	v_readfirstlane_b32 s99, v181
	v_readfirstlane_b32 s100, v182
	v_readfirstlane_b32 s101, v183
	s_branch .Lkl_ptr_done

; #define PG8_STAGE(bufoff, gbase, voff) do { _Pragma("unroll") for (int _i = 0; _i < 2; ++_i) \
;         __builtin_amdgcn_global_load_lds((const unsigned*)((const char*)(gbase) + (voff)[_i]), (LAS unsigned*)(lds + (bufoff) + ldsw + _i * 8192), 16, 0, 0); } while (0)
; #define PG8_LDA(dst, b, h) do { _Pragma("unroll") for (int m = 0; m < 4; ++m) _Pragma("unroll") for (int k = 0; k < 2; ++k) dst[m][k] = *(const LAS bf16x8*)(lds + PG8_SA(b, h) + aoff + m * 2048 + k * 1024); } while (0)
; #define PG8_LDB(dst, b, h) do { _Pragma("unroll") for (int n = 0; n < 2; ++n) _Pragma("unroll") for (int k = 0; k < 2; ++k) dst[n][k] = *(const LAS bf16x8*)(lds + PG8_SB(b, h) + boff + n * 2048 + k * 1024); } while (0)
; #define PG8_MMA(ai, bj, At, Bt) do { __builtin_amdgcn_s_setprio(1); _Pragma("unroll") for (int m = 0; m < 4; ++m) _Pragma("unroll") for (int n = 0; n < 2; ++n) _Pragma("unroll") for (int k = 0; k < 2; ++k) \
;         acc[ai][bj][m][n] = __builtin_amdgcn_mfma_f32_16x16x32_bf16(Bt[n][k], At[m][k], acc[ai][bj][m][n], 0, 0, 0); __builtin_amdgcn_s_setprio(0); } while (0)
; #define PG8_WAIT_V(n) asm volatile("s_waitcnt vmcnt(" #n ")" ::: "memory")
; #define PG8_WAIT_L(n) asm volatile("s_waitcnt lgkmcnt(" #n ")" ::: "memory")
; #define PG8_BAR __builtin_amdgcn_s_barrier()
; #define PG8_SCHED __builtin_amdgcn_sched_barrier(0)
; __device__ __forceinline__ void gemm_phase(LAS unsigned char* lds, const GemmD& g) {
;     ...
;             PG8_LDB(B1, 0, 1); PG8_STAGE(PG8_SB(0, 0), b2, voffB);
;             PG8_BAR; PG8_WAIT_L(0); PG8_MMA(0, 1, At, B1); PG8_BAR;
;             PG8_LDA(At, 0, 1); PG8_STAGE(PG8_SA(0, 0), a2, voffA);
;             PG8_BAR; PG8_WAIT_L(0); PG8_MMA(1, 0, At, B0); PG8_BAR; PG8_SCHED;
;             PG8_STAGE(PG8_SB(0, 1), b2 + hstep, voffB);
;             PG8_WAIT_V(6); PG8_BAR; PG8_MMA(1, 1, At, B1); PG8_BAR;
;             PG8_LDB(B0, 1, 0); PG8_SCHED; PG8_LDA(At, 1, 0); PG8_STAGE(PG8_SA(0, 1), a2 + hstep, voffA);
;             PG8_WAIT_L(8); PG8_BAR; PG8_WAIT_L(0); PG8_MMA(0, 0, At, B0); PG8_BAR; PG8_SCHED;
.Lkl_ptr_done:
	s_add_i32 s4, 0, 0x14000
	s_add_i32 s6, s87, 0x10000
	s_mov_b32 m0, s6
	ds_read_b128 v[204:207], v245
	ds_read_b128 v[208:211], v245 offset:1024
	ds_read_b128 v[234:237], v245 offset:2048
	ds_read_b128 v[238:241], v245 offset:3072
	global_load_lds_dwordx4 v172, s[100:101]
	s_add_i32 m0, s6, 0x2000
	s_nop 0
	global_load_lds_dwordx4 v168, s[100:101]
	s_barrier
	s_waitcnt lgkmcnt(0)
	v_mfma_f32_16x16x32_bf16 v[118:121], v[204:207], v[152:155], v[118:121]
	v_mfma_f32_16x16x32_bf16 v[114:117], v[234:237], v[152:155], v[114:117]
	v_mfma_f32_16x16x32_bf16 v[102:105], v[204:207], v[160:163], v[102:105]
	v_mfma_f32_16x16x32_bf16 v[98:101], v[234:237], v[160:163], v[98:101]
	v_mfma_f32_16x16x32_bf16 v[86:89], v[204:207], v[188:191], v[86:89]
	v_mfma_f32_16x16x32_bf16 v[82:85], v[234:237], v[188:191], v[82:85]
	v_mfma_f32_16x16x32_bf16 v[70:73], v[204:207], v[196:199], v[70:73]
	v_mfma_f32_16x16x32_bf16 v[66:69], v[234:237], v[196:199], v[66:69]
	v_mfma_f32_16x16x32_bf16 v[118:121], v[208:211], v[156:159], v[118:121]
	v_mfma_f32_16x16x32_bf16 v[114:117], v[238:241], v[156:159], v[114:117]
	v_mfma_f32_16x16x32_bf16 v[102:105], v[208:211], v[184:187], v[102:105]
	v_mfma_f32_16x16x32_bf16 v[98:101], v[238:241], v[184:187], v[98:101]
	v_mfma_f32_16x16x32_bf16 v[86:89], v[208:211], v[192:195], v[86:89]
	v_mfma_f32_16x16x32_bf16 v[82:85], v[238:241], v[192:195], v[82:85]
	v_mfma_f32_16x16x32_bf16 v[70:73], v[208:211], v[200:203], v[70:73]
	v_mfma_f32_16x16x32_bf16 v[66:69], v[238:241], v[200:203], v[66:69]
	s_barrier
	s_mov_b32 m0, s2
	ds_read_b128 v[152:155], v233 offset:16384
	ds_read_b128 v[156:159], v233 offset:17408
	ds_read_b128 v[160:163], v233 offset:18432
	ds_read_b128 v[184:187], v233 offset:19456
	ds_read_b128 v[188:191], v233 offset:20480
	ds_read_b128 v[192:195], v233 offset:21504
	ds_read_b128 v[196:199], v233 offset:22528
	ds_read_b128 v[200:203], v233 offset:23552
	global_load_lds_dwordx4 v170, s[98:99]
	s_mov_b32 m0, s3
	s_nop 0
	global_load_lds_dwordx4 v166, s[98:99]
	s_barrier
	s_waitcnt lgkmcnt(0)
	v_mfma_f32_16x16x32_bf16 v[62:65], v[136:139], v[152:155], v[62:65]
	v_mfma_f32_16x16x32_bf16 v[58:61], v[144:147], v[152:155], v[58:61]
	v_mfma_f32_16x16x32_bf16 v[46:49], v[136:139], v[160:163], v[46:49]
	v_mfma_f32_16x16x32_bf16 v[42:45], v[144:147], v[160:163], v[42:45]
	v_mfma_f32_16x16x32_bf16 v[30:33], v[136:139], v[188:191], v[30:33]
	v_mfma_f32_16x16x32_bf16 v[26:29], v[144:147], v[188:191], v[26:29]
	v_mfma_f32_16x16x32_bf16 v[14:17], v[136:139], v[196:199], v[14:17]
	v_mfma_f32_16x16x32_bf16 v[10:13], v[144:147], v[196:199], v[10:13]
	v_mfma_f32_16x16x32_bf16 v[62:65], v[140:143], v[156:159], v[62:65]
	v_mfma_f32_16x16x32_bf16 v[58:61], v[148:151], v[156:159], v[58:61]
	v_mfma_f32_16x16x32_bf16 v[46:49], v[140:143], v[184:187], v[46:49]
	v_mfma_f32_16x16x32_bf16 v[42:45], v[148:151], v[184:187], v[42:45]
	v_mfma_f32_16x16x32_bf16 v[30:33], v[140:143], v[192:195], v[30:33]
	v_mfma_f32_16x16x32_bf16 v[26:29], v[148:151], v[192:195], v[26:29]
	v_mfma_f32_16x16x32_bf16 v[14:17], v[140:143], v[200:203], v[14:17]
	v_mfma_f32_16x16x32_bf16 v[10:13], v[148:151], v[200:203], v[10:13]
	s_barrier
	s_add_i32 s4, s4, s87
	s_mov_b32 m0, s4
	s_nop 0
	global_load_lds_dwordx4 v242, s[100:101]
	s_add_i32 m0, s4, 0x2000
	s_nop 0
	global_load_lds_dwordx4 v243, s[100:101]
	s_waitcnt vmcnt(6)
	s_barrier
	v_mfma_f32_16x16x32_bf16 v[54:57], v[204:207], v[152:155], v[54:57]
	v_mfma_f32_16x16x32_bf16 v[50:53], v[234:237], v[152:155], v[50:53]
	v_mfma_f32_16x16x32_bf16 v[38:41], v[204:207], v[160:163], v[38:41]
	v_mfma_f32_16x16x32_bf16 v[34:37], v[234:237], v[160:163], v[34:37]
	v_mfma_f32_16x16x32_bf16 v[22:25], v[204:207], v[188:191], v[22:25]
	v_mfma_f32_16x16x32_bf16 v[18:21], v[234:237], v[188:191], v[18:21]
	v_mfma_f32_16x16x32_bf16 v[6:9], v[204:207], v[196:199], v[6:9]
	v_mfma_f32_16x16x32_bf16 v[2:5], v[234:237], v[196:199], v[2:5]
	v_mfma_f32_16x16x32_bf16 v[54:57], v[208:211], v[156:159], v[54:57]
	v_mfma_f32_16x16x32_bf16 v[50:53], v[238:241], v[156:159], v[50:53]
	v_mfma_f32_16x16x32_bf16 v[38:41], v[208:211], v[184:187], v[38:41]
	v_mfma_f32_16x16x32_bf16 v[34:37], v[238:241], v[184:187], v[34:37]
	v_mfma_f32_16x16x32_bf16 v[22:25], v[208:211], v[192:195], v[22:25]
	v_mfma_f32_16x16x32_bf16 v[18:21], v[238:241], v[192:195], v[18:21]
	v_mfma_f32_16x16x32_bf16 v[6:9], v[208:211], v[200:203], v[6:9]
	v_mfma_f32_16x16x32_bf16 v[2:5], v[238:241], v[200:203], v[2:5]
	s_barrier
	ds_read_b128 v[136:139], v246
	ds_read_b128 v[140:143], v246 offset:1024
	ds_read_b128 v[144:147], v246 offset:2048
	ds_read_b128 v[148:151], v246 offset:3072
	s_mov_b32 m0, s64
	ds_read_b128 v[152:155], v233 offset:32768
	ds_read_b128 v[156:159], v233 offset:33792
	ds_read_b128 v[160:163], v233 offset:34816
	ds_read_b128 v[184:187], v233 offset:35840
	ds_read_b128 v[188:191], v233 offset:36864
	ds_read_b128 v[192:195], v233 offset:37888
	ds_read_b128 v[196:199], v233 offset:38912
	ds_read_b128 v[200:203], v233 offset:39936
	global_load_lds_dwordx4 v174, s[98:99]
	s_mov_b32 m0, s65
	s_nop 0
	global_load_lds_dwordx4 v176, s[98:99]
	s_waitcnt lgkmcnt(8)
	s_barrier
; #define PG8_STAGE(bufoff, gbase, voff) do { _Pragma("unroll") for (int _i = 0; _i < 2; ++_i) \
;         __builtin_amdgcn_global_load_lds((const unsigned*)((const char*)(gbase) + (voff)[_i]), (LAS unsigned*)(lds + (bufoff) + ldsw + _i * 8192), 16, 0, 0); } while (0)
; #define PG8_LDA(dst, b, h) do { _Pragma("unroll") for (int m = 0; m < 4; ++m) _Pragma("unroll") for (int k = 0; k < 2; ++k) dst[m][k] = *(const LAS bf16x8*)(lds + PG8_SA(b, h) + aoff + m * 2048 + k * 1024); } while (0)
; #define PG8_LDB(dst, b, h) do { _Pragma("unroll") for (int n = 0; n < 2; ++n) _Pragma("unroll") for (int k = 0; k < 2; ++k) dst[n][k] = *(const LAS bf16x8*)(lds + PG8_SB(b, h) + boff + n * 2048 + k * 1024); } while (0)
; #define PG8_MMA(ai, bj, At, Bt) do { __builtin_amdgcn_s_setprio(1); _Pragma("unroll") for (int m = 0; m < 4; ++m) _Pragma("unroll") for (int n = 0; n < 2; ++n) _Pragma("unroll") for (int k = 0; k < 2; ++k) \
;         acc[ai][bj][m][n] = __builtin_amdgcn_mfma_f32_16x16x32_bf16(Bt[n][k], At[m][k], acc[ai][bj][m][n], 0, 0, 0); __builtin_amdgcn_s_setprio(0); } while (0)
; #define PG8_WAIT_V(n) asm volatile("s_waitcnt vmcnt(" #n ")" ::: "memory")
; #define PG8_WAIT_L(n) asm volatile("s_waitcnt lgkmcnt(" #n ")" ::: "memory")
; #define PG8_BAR __builtin_amdgcn_s_barrier()
; #define PG8_SCHED __builtin_amdgcn_sched_barrier(0)
; __device__ __forceinline__ void gemm_epilogue(const GemmD& g, const f32x4 (&acc)[2][2][4][2], const Unit& u, int wr, int wc, int fr, int fq) {
;     const int row0 = u.pm * BM + wr * 64 + fr;
;     const int mode = g.mode;
;     if (u.part >= 0) {
; __device__ __forceinline__ void gemm_phase(LAS unsigned char* lds, const GemmD& g) {
;     ...
;             PG8_WAIT_L(8); PG8_BAR; PG8_WAIT_L(0); PG8_MMA(0, 0, At, B0); PG8_BAR; PG8_SCHED;
;             PG8_LDB(B1, 1, 1); PG8_STAGE(PG8_SB(1, 0), b3, voffB);
;             PG8_BAR; PG8_WAIT_L(0); PG8_MMA(0, 1, At, B1); PG8_BAR;
;             PG8_LDA(At, 1, 1); PG8_STAGE(PG8_SA(1, 0), a3, voffA);
;             PG8_BAR; PG8_WAIT_L(0); PG8_MMA(1, 0, At, B0); PG8_BAR; PG8_SCHED;
;             PG8_STAGE(PG8_SB(1, 1), b3 + hstep, voffB);
;             PG8_WAIT_V(6); PG8_BAR; PG8_MMA(1, 1, At, B1); PG8_BAR;
;         }
	s_waitcnt lgkmcnt(0)
	v_mfma_f32_16x16x32_bf16 v[126:129], v[136:139], v[152:155], v[126:129]
	v_mfma_f32_16x16x32_bf16 v[122:125], v[144:147], v[152:155], v[122:125]
	v_mfma_f32_16x16x32_bf16 v[110:113], v[136:139], v[160:163], v[110:113]
	v_mfma_f32_16x16x32_bf16 v[106:109], v[144:147], v[160:163], v[106:109]
	v_mfma_f32_16x16x32_bf16 v[94:97], v[136:139], v[188:191], v[94:97]
	v_mfma_f32_16x16x32_bf16 v[90:93], v[144:147], v[188:191], v[90:93]
	v_mfma_f32_16x16x32_bf16 v[78:81], v[136:139], v[196:199], v[78:81]
	v_mfma_f32_16x16x32_bf16 v[74:77], v[144:147], v[196:199], v[74:77]
	v_mfma_f32_16x16x32_bf16 v[126:129], v[140:143], v[156:159], v[126:129]
	v_mfma_f32_16x16x32_bf16 v[122:125], v[148:151], v[156:159], v[122:125]
	v_mfma_f32_16x16x32_bf16 v[110:113], v[140:143], v[184:187], v[110:113]
	v_mfma_f32_16x16x32_bf16 v[106:109], v[148:151], v[184:187], v[106:109]
	v_mfma_f32_16x16x32_bf16 v[94:97], v[140:143], v[192:195], v[94:97]
	v_mfma_f32_16x16x32_bf16 v[90:93], v[148:151], v[192:195], v[90:93]
	v_mfma_f32_16x16x32_bf16 v[78:81], v[140:143], v[200:203], v[78:81]
	v_mfma_f32_16x16x32_bf16 v[74:77], v[148:151], v[200:203], v[74:77]
	s_barrier
	s_add_i32 s6, 0, 0x1c000
	s_add_i32 s4, s87, 0x18000
	ds_read_b128 v[204:207], v247
	ds_read_b128 v[208:211], v247 offset:1024
	ds_read_b128 v[234:237], v247 offset:2048
	ds_read_b128 v[238:241], v247 offset:3072
	s_add_u32 s100, s100, 0x80
	s_addc_u32 s101, s101, 0
	s_mov_b32 m0, s4
	s_nop 0
	global_load_lds_dwordx4 v172, s[100:101]
	s_add_i32 m0, s4, 0x2000
	s_nop 0
	global_load_lds_dwordx4 v168, s[100:101]
	s_barrier
	s_waitcnt lgkmcnt(0)
	v_mfma_f32_16x16x32_bf16 v[118:121], v[204:207], v[152:155], v[118:121]
	v_mfma_f32_16x16x32_bf16 v[114:117], v[234:237], v[152:155], v[114:117]
	v_mfma_f32_16x16x32_bf16 v[102:105], v[204:207], v[160:163], v[102:105]
	v_mfma_f32_16x16x32_bf16 v[98:101], v[234:237], v[160:163], v[98:101]
	v_mfma_f32_16x16x32_bf16 v[86:89], v[204:207], v[188:191], v[86:89]
	v_mfma_f32_16x16x32_bf16 v[82:85], v[234:237], v[188:191], v[82:85]
	v_mfma_f32_16x16x32_bf16 v[70:73], v[204:207], v[196:199], v[70:73]
	v_mfma_f32_16x16x32_bf16 v[66:69], v[234:237], v[196:199], v[66:69]
	v_mfma_f32_16x16x32_bf16 v[118:121], v[208:211], v[156:159], v[118:121]
	v_mfma_f32_16x16x32_bf16 v[114:117], v[238:241], v[156:159], v[114:117]
	v_mfma_f32_16x16x32_bf16 v[102:105], v[208:211], v[184:187], v[102:105]
	v_mfma_f32_16x16x32_bf16 v[98:101], v[238:241], v[184:187], v[98:101]
	v_mfma_f32_16x16x32_bf16 v[86:89], v[208:211], v[192:195], v[86:89]
	v_mfma_f32_16x16x32_bf16 v[82:85], v[238:241], v[192:195], v[82:85]
	v_mfma_f32_16x16x32_bf16 v[70:73], v[208:211], v[200:203], v[70:73]
	v_mfma_f32_16x16x32_bf16 v[66:69], v[238:241], v[200:203], v[66:69]
	s_barrier
	s_mov_b32 m0, s28
	s_add_u32 s98, s98, 0x80
	s_addc_u32 s99, s99, 0
	ds_read_b128 v[152:155], v233 offset:49152
	ds_read_b128 v[156:159], v233 offset:50176
	ds_read_b128 v[160:163], v233 offset:51200
	ds_read_b128 v[184:187], v233 offset:52224
	ds_read_b128 v[188:191], v233 offset:53248
	ds_read_b128 v[192:195], v233 offset:54272
	ds_read_b128 v[196:199], v233 offset:55296
	ds_read_b128 v[200:203], v233 offset:56320
	global_load_lds_dwordx4 v170, s[98:99]
	s_mov_b32 m0, s29
	s_nop 0
	global_load_lds_dwordx4 v166, s[98:99]
	s_barrier
	s_waitcnt lgkmcnt(0)
	v_mfma_f32_16x16x32_bf16 v[62:65], v[136:139], v[152:155], v[62:65]
	v_mfma_f32_16x16x32_bf16 v[58:61], v[144:147], v[152:155], v[58:61]
	v_mfma_f32_16x16x32_bf16 v[46:49], v[136:139], v[160:163], v[46:49]
	v_mfma_f32_16x16x32_bf16 v[42:45], v[144:147], v[160:163], v[42:45]
	v_mfma_f32_16x16x32_bf16 v[30:33], v[136:139], v[188:191], v[30:33]
	v_mfma_f32_16x16x32_bf16 v[26:29], v[144:147], v[188:191], v[26:29]
	v_mfma_f32_16x16x32_bf16 v[14:17], v[136:139], v[196:199], v[14:17]
	v_mfma_f32_16x16x32_bf16 v[10:13], v[144:147], v[196:199], v[10:13]
	v_mfma_f32_16x16x32_bf16 v[62:65], v[140:143], v[156:159], v[62:65]
	v_mfma_f32_16x16x32_bf16 v[58:61], v[148:151], v[156:159], v[58:61]
	v_mfma_f32_16x16x32_bf16 v[46:49], v[140:143], v[184:187], v[46:49]
	v_mfma_f32_16x16x32_bf16 v[42:45], v[148:151], v[184:187], v[42:45]
	v_mfma_f32_16x16x32_bf16 v[30:33], v[140:143], v[192:195], v[30:33]
	v_mfma_f32_16x16x32_bf16 v[26:29], v[148:151], v[192:195], v[26:29]
	v_mfma_f32_16x16x32_bf16 v[14:17], v[140:143], v[200:203], v[14:17]
	v_mfma_f32_16x16x32_bf16 v[10:13], v[148:151], v[200:203], v[10:13]
	s_barrier
	s_add_i32 s4, s6, s87
	s_mov_b32 m0, s4
	s_nop 0
	global_load_lds_dwordx4 v242, s[100:101]
	s_add_i32 m0, s4, 0x2000
	s_nop 0
	global_load_lds_dwordx4 v243, s[100:101]
	s_add_u32 s100, s100, 0x80
	s_addc_u32 s101, s101, 0
	s_mov_b32 s4, s5
	s_waitcnt vmcnt(6)
	s_barrier
	v_mfma_f32_16x16x32_bf16 v[54:57], v[204:207], v[152:155], v[54:57]
	v_mfma_f32_16x16x32_bf16 v[50:53], v[234:237], v[152:155], v[50:53]
	v_mfma_f32_16x16x32_bf16 v[38:41], v[204:207], v[160:163], v[38:41]
	v_mfma_f32_16x16x32_bf16 v[34:37], v[234:237], v[160:163], v[34:37]
	v_mfma_f32_16x16x32_bf16 v[22:25], v[204:207], v[188:191], v[22:25]
	v_mfma_f32_16x16x32_bf16 v[18:21], v[234:237], v[188:191], v[18:21]
	v_mfma_f32_16x16x32_bf16 v[6:9], v[204:207], v[196:199], v[6:9]
	v_mfma_f32_16x16x32_bf16 v[2:5], v[234:237], v[196:199], v[2:5]
	v_mfma_f32_16x16x32_bf16 v[54:57], v[208:211], v[156:159], v[54:57]
	v_mfma_f32_16x16x32_bf16 v[50:53], v[238:241], v[156:159], v[50:53]
	v_mfma_f32_16x16x32_bf16 v[38:41], v[208:211], v[184:187], v[38:41]
	v_mfma_f32_16x16x32_bf16 v[34:37], v[238:241], v[184:187], v[34:37]
	v_mfma_f32_16x16x32_bf16 v[22:25], v[208:211], v[192:195], v[22:25]
	v_mfma_f32_16x16x32_bf16 v[18:21], v[238:241], v[192:195], v[18:21]
	v_mfma_f32_16x16x32_bf16 v[6:9], v[208:211], v[200:203], v[6:9]
	v_mfma_f32_16x16x32_bf16 v[2:5], v[238:241], v[200:203], v[2:5]
	s_barrier
	s_cbranch_vccz .LBB0_145
	v_lshl_add_u32 v184, s56, 8, v228
	s_cmp_lt_i32 s66, 0
	s_mov_b64 s[4:5], -1
	s_cbranch_scc0 .LBB0_704
